# PEER phases: work items assigned XCD-contiguously (all heads of a token on one XCD)
# baseline (speedup 1.0000x reference)
.LBB0_2089:
	v_readlane_b32 s98, v245, 0
	v_readlane_b32 s99, v245, 9
	s_nop 3
	v_writelane_b32 v244, s98, 63
	s_cmpk_lg_u32 s99, 0x200
	s_cbranch_scc1 .Lpxa_go
	s_and_b32 s99, s98, 7
	s_lshl_b32 s99, s99, 6
	s_lshr_b32 s98, s98, 3
	s_or_b32 s99, s99, s98
	s_nop 0
	v_writelane_b32 v245, s99, 0
	s_nop 1

.Lpxa_end:
	v_readlane_b32 s98, v244, 63
	s_nop 3
	v_writelane_b32 v245, s98, 0
	s_nop 1
